# assumption: the cache invalidate at unit admission is redundant (all data read after an admission was last cached before the latest grid-barrier acquire; producers write through) - removed both buffer
# speedup vs baseline: 1.0517x; 1.0099x over previous
.LBB0_214:
	s_waitcnt vmcnt(0)
	s_waitcnt vmcnt(0)
	v_cmp_eq_u32_e32 vcc, 0, v131
	s_and_b64 exec, exec, vcc
	v_mov_b32_e32 v112, s79
	ds_write_b32 v112, v246

.LBB0_398:
	s_or_b64 exec, exec, s[34:35]
	v_cndmask_b32_e64 v112, 0, 1, s[36:37]
	v_cmp_ne_u32_e32 vcc, 0, v112
	s_cmp_eq_u64 vcc, exec
	s_waitcnt lgkmcnt(0)
	s_cselect_b64 s[6:7], -1, 0
	s_cmp_lg_u64 vcc, exec
	s_cbranch_scc1 .LBB0_400
	s_waitcnt vmcnt(0)
	s_waitcnt vmcnt(0)
